# cache-policy: nt also on the p->bf16 prologue stores (consumed two phases later)
# baseline (speedup 1.0000x reference)
; __device__ __forceinline__ unsigned pk2(float lo, float hi) { f32x2_t v = {lo, hi}; bf16x2_t b = __builtin_convertvector(v, bf16x2_t); return __builtin_bit_cast(unsigned, b); }
; __device__ __forceinline__ void p_rows2(const float* prow, u16* PBo, int gw, int NGW, int lane) {
;     for (int m = gw; m < 2 * MTOK; m += NGW) {
;         if (lane < 32) { const f32x4 a = ((const f32x4*)(prow + (size_t)m * 256))[2 * lane], b = ((const f32x4*)(prow + (size_t)m * 256))[2 * lane + 1];
;             v4u w; w.x = pk2(a[0], a[1]); w.y = pk2(a[2], a[3]); w.z = pk2(b[0], b[1]); w.w = pk2(b[2], b[3]); ((v4u*)(PBo + (size_t)m * 256))[lane] = w; }
;     }
.LBB0_117:
	s_and_saveexec_b64 s[8:9], vcc
	s_cbranch_execz .LBB0_116
	global_load_dwordx4 v[6:9], v[2:3], off offset:-16 nt
	global_load_dwordx4 v[10:13], v[2:3], off nt
	s_waitcnt vmcnt(1)
	v_cvt_pk_bf16_f32 v6, v6, v7
	v_cvt_pk_bf16_f32 v7, v8, v9
	s_waitcnt vmcnt(0)
	v_cvt_pk_bf16_f32 v8, v10, v11
	v_cvt_pk_bf16_f32 v9, v12, v13
	global_store_dwordx4 v[4:5], v[6:9], off nt
	s_branch .LBB0_116
